# code placement: one 4-byte nop at the MLA-attention phase entry (shifts later hot loops by 4 B; loop head of the MLA inner loop now 8-B aligned)
# speedup vs baseline: 1.0032x; 1.0032x over previous
; __device__ void phase_attn_mla(const Params& p, char* lds, int* s_item, int dry) {
;   const int x = blockIdx.x & 7;
;   const int total = 256 + 16;
;   unsigned* q = (unsigned*)(p.ws + W_BAR) + QW + 16 + dry * 8 + x;
;   for (;;) {
;     if (threadIdx.x == 0) *s_item = (int)__hip_atomic_fetch_add(q, 1u, __ATOMIC_RELAXED, __HIP_MEMORY_SCOPE_AGENT);
.LBB0_649:
	s_cmp_gt_i32 s24, 5
	s_cselect_b64 s[0:1], -1, 0
	s_cmp_lt_i32 s25, 6
	s_cselect_b64 s[2:3], -1, 0
	s_or_b64 s[0:1], s[0:1], s[2:3]
	s_and_b64 vcc, exec, s[0:1]
	s_cbranch_vccnz .LBB0_780
	v_readlane_b32 s0, v248, 33
	s_and_b32 s33, s0, 7
	s_nop 0
	s_bfe_u32 s16, s26, 0x10005
	s_lshl_b32 s0, s33, 2
	s_add_u32 s0, s96, s0
	s_addc_u32 s1, s97, 0
	s_add_u32 s0, s0, 0x166d840
	v_writelane_b32 v248, s0, 27
	s_addc_u32 s0, s1, 0
	s_add_u32 s24, s96, 0x166e000
	s_addc_u32 s25, s97, 0
	s_add_u32 s26, s96, 0x1699e000
	s_addc_u32 s27, s97, 0
	s_add_u32 s12, s96, 0x15e8000
	s_addc_u32 s13, s97, 0
	s_add_u32 s28, s96, 0xa08e000
	s_addc_u32 s29, s97, 0
	v_writelane_b32 v248, s0, 56
	s_add_u32 s30, s96, 0x1bfde000
	s_addc_u32 s31, s97, 0
	v_readlane_b32 s0, v248, 0
	v_readlane_b32 s1, v248, 1
	s_add_u32 s10, s0, 0xf0
	s_addc_u32 s11, s1, 0
	s_add_u32 s78, s96, 0x166a400
	s_addc_u32 s79, s97, 0
	v_readlane_b32 s0, v248, 8
	s_cmp_eq_u32 s0, 0
	s_cselect_b64 s[2:3], -1, 0
	s_add_u32 s80, s96, 0x166a500
	s_addc_u32 s81, s97, 0
	v_writelane_b32 v248, s2, 54
	s_cmp_eq_u32 s0, 1
	s_movk_i32 s18, 0xff80
	v_writelane_b32 v248, s3, 55
	s_cselect_b64 s[2:3], -1, 0
	s_add_u32 s82, s96, 0x166a600
	s_addc_u32 s83, s97, 0
	v_writelane_b32 v248, s2, 58
	s_cmp_eq_u32 s0, 2
	v_mov_b32_e32 v1, 0
	v_writelane_b32 v248, s3, 59
	s_cselect_b64 s[2:3], -1, 0
	s_add_u32 s84, s96, 0x166a700
	s_addc_u32 s85, s97, 0
	v_writelane_b32 v248, s2, 62
	s_cmp_eq_u32 s0, 3
	v_mov_b32_e32 v183, 0x12310
	v_writelane_b32 v248, s3, 63
	s_cselect_b64 s[2:3], -1, 0
	s_add_u32 s86, s96, 0x166a800
	s_addc_u32 s87, s97, 0
	v_writelane_b32 v247, s2, 2
	s_cmp_eq_u32 s0, 4
	v_mov_b32_e32 v187, 0x40000
	v_writelane_b32 v247, s3, 3
	s_cselect_b64 s[2:3], -1, 0
	s_add_u32 s88, s96, 0x166a900
	s_addc_u32 s89, s97, 0
	v_writelane_b32 v247, s2, 6
	s_cmp_eq_u32 s0, 5
	v_mbcnt_hi_u32_b32 v234, -1, v221
	v_writelane_b32 v247, s3, 7
	s_cselect_b64 s[2:3], -1, 0
	s_add_u32 s90, s96, 0x166aa00
	s_addc_u32 s91, s97, 0
	v_writelane_b32 v247, s2, 10
	s_cmp_eq_u32 s0, 6
	v_mov_b32_e32 v190, 0x12300
	v_writelane_b32 v247, s3, 11
	s_cselect_b64 s[2:3], -1, 0
	s_add_u32 s92, s96, 0x166ab00
	s_addc_u32 s93, s97, 0
	v_writelane_b32 v247, s2, 14
	s_cmp_eq_u32 s0, 7
	v_mov_b32_e32 v192, 0x12304
	v_writelane_b32 v247, s3, 15
	s_cselect_b64 s[2:3], -1, 0
	s_add_u32 s94, s96, 0x166ac00
	s_addc_u32 s95, s97, 0
	v_writelane_b32 v247, s2, 18
	s_cmp_eq_u32 s0, 8
	s_movk_i32 s34, 0x880
	v_writelane_b32 v247, s3, 19
	s_cselect_b64 s[2:3], -1, 0
	s_add_u32 s76, s96, 0x166ad00
	s_addc_u32 s77, s97, 0
	v_writelane_b32 v247, s2, 22
	s_cmp_eq_u32 s0, 9
	s_mov_b32 s35, 0x2aaaaaab
	v_writelane_b32 v247, s3, 23
	s_cselect_b64 s[2:3], -1, 0
	s_add_u32 s74, s96, 0x166ae00
	s_addc_u32 s75, s97, 0
	v_writelane_b32 v247, s2, 26
	s_cmp_eq_u32 s0, 10
	s_movk_i32 s36, 0xd0
	v_writelane_b32 v247, s3, 27
	s_cselect_b64 s[2:3], -1, 0
	s_add_u32 s4, s96, 0x166af00
	s_addc_u32 s5, s97, 0
	v_writelane_b32 v247, s2, 30
	s_cmp_eq_u32 s0, 11
	s_movk_i32 s37, 0x90
	v_writelane_b32 v247, s3, 31
	s_cselect_b64 s[2:3], -1, 0
	s_add_u32 s6, s96, 0x166b000
	s_addc_u32 s7, s97, 0
	v_writelane_b32 v247, s2, 34
	s_cmp_eq_u32 s0, 12
	s_mov_b32 s22, 0
	v_writelane_b32 v247, s3, 35
	s_cselect_b64 s[2:3], -1, 0
	s_add_u32 s14, s96, 0x166b100
	s_addc_u32 s15, s97, 0
	v_writelane_b32 v247, s2, 38
	s_cmp_eq_u32 s0, 13
	s_mov_b32 s17, 0
	v_writelane_b32 v247, s3, 39
	s_cselect_b64 s[2:3], -1, 0
	s_add_u32 s20, s96, 0x166b200
	s_addc_u32 s21, s97, 0
	v_writelane_b32 v247, s2, 42
	s_cmp_eq_u32 s0, 14
	s_mov_b32 s19, -1
	v_writelane_b32 v247, s3, 43
	s_cselect_b64 s[2:3], -1, 0
	s_add_u32 s8, s96, 0x166b300
	s_addc_u32 s9, s97, 0
	v_writelane_b32 v247, s2, 46
	s_cmp_eq_u32 s0, 15
	v_writelane_b32 v246, s16, 14
	v_writelane_b32 v247, s3, 47
	s_cselect_b64 s[2:3], -1, 0
	v_writelane_b32 v247, s2, 50
	s_lshl_b32 s0, s0, 8
	s_nop 0
	v_writelane_b32 v247, s3, 51
	v_readlane_b32 s2, v248, 6
	v_readlane_b32 s3, v248, 7
	s_add_u32 s0, s2, s0
	s_addc_u32 s1, s3, 0
	s_add_u32 s2, s0, 0x1400
	s_addc_u32 s3, s1, 0
	s_add_u32 s68, s0, 0x2400
	s_addc_u32 s69, s1, 0
	v_writelane_b32 v247, s2, 4
	s_add_u32 s0, s96, 0x166d400
	s_addc_u32 s1, s97, 0
	v_writelane_b32 v247, s3, 5
	v_writelane_b32 v247, s0, 8
	s_add_u32 s70, s96, 0x166d500
	s_addc_u32 s71, s97, 0
	v_writelane_b32 v247, s1, 9
	v_writelane_b32 v248, s68, 60
	v_writelane_b32 v247, s70, 0
	s_nop 0
	v_writelane_b32 v248, s69, 61
	v_writelane_b32 v247, s71, 1
	s_branch .LBB0_654
